# v23 + nt removed from the 16 norm-gain vector loads in the w_in / w_up transposes (small hot arrays stay cached)
# speedup vs baseline: 1.0020x; 1.0020x over previous
; __device__ __forceinline__ void transpose_w(const int wv, LAS unsigned char* lds, const float* __restrict__ w, bf16_t* __restrict__ wt, int K, int N, const float* __restrict__ gk, int slo, int shi, float scale) {
;     ...
;         float v[8];
; #pragma unroll
;         for (int j = 0; j < 8; ++j) { float g = gk ? gk[k0 + j] : 1.0f; v[j] = w[(size_t)(k0 + j) * N + n] * g; }
; __global__ void __launch_bounds__(512, 2) mega(Params p_unused) {
;     ...
;         transpose_w(wv, lds, kp->w_in, WSP(bf16_t, WS_WIN), DM, INW, kp->norm1_g, C_RK, C_RK + 1024, 0.0625f);
.LBB0_10:
	s_lshl_b32 s17, s17, 6
	v_or_b32_e32 v8, s17, v10
	v_ashrrev_i32_e32 v9, 31, v8
	v_lshl_add_u64 v[8:9], v[8:9], 2, s[6:7]
	v_mad_i64_i32 v[16:17], s[20:21], v4, s15, v[8:9]
	global_load_dword v16, v[16:17], off nt
	s_and_b64 vcc, exec, s[0:1]
	s_cbranch_vccnz .LBB0_12
	global_load_dword v15, v[6:7], off offset:4
.LBB0_12:
	v_add_u32_e32 v17, 1, v4
	v_mad_i64_i32 v[18:19], s[20:21], v17, s15, v[8:9]
	global_load_dword v18, v[18:19], off nt
	v_mov_b32_e32 v19, 1.0
	s_and_b64 vcc, exec, s[0:1]
	v_mov_b32_e32 v20, 1.0
	s_cbranch_vccnz .LBB0_14
	global_load_dword v20, v[6:7], off offset:8
.LBB0_14:
	v_add_u32_e32 v17, 2, v4
	v_mad_i64_i32 v[22:23], s[20:21], v17, s15, v[8:9]
	global_load_dword v21, v[22:23], off nt
	s_and_b64 vcc, exec, s[0:1]
	s_cbranch_vccnz .LBB0_16
	global_load_dword v19, v[6:7], off offset:12
.LBB0_16:
	v_add_u32_e32 v17, 3, v4
	v_mad_i64_i32 v[22:23], s[20:21], v17, s15, v[8:9]
	global_load_dword v22, v[22:23], off nt
	v_mov_b32_e32 v23, 1.0
	s_and_b64 vcc, exec, s[0:1]
	v_mov_b32_e32 v24, 1.0
	s_cbranch_vccnz .LBB0_18
	global_load_dword v24, v[6:7], off offset:16
.LBB0_18:
	v_add_u32_e32 v17, 4, v4
	v_mad_i64_i32 v[26:27], s[20:21], v17, s15, v[8:9]
	global_load_dword v25, v[26:27], off nt
	s_and_b64 vcc, exec, s[0:1]
	s_cbranch_vccnz .LBB0_20
	global_load_dword v23, v[6:7], off offset:20
.LBB0_20:
	v_add_u32_e32 v17, 5, v4
	v_mad_i64_i32 v[26:27], s[20:21], v17, s15, v[8:9]
	global_load_dword v26, v[26:27], off nt
	v_mov_b32_e32 v17, 1.0
	s_and_b64 vcc, exec, s[0:1]
	v_mov_b32_e32 v27, 1.0
	s_cbranch_vccnz .LBB0_22
	global_load_dword v27, v[6:7], off offset:24
.LBB0_22:
	v_add_u32_e32 v28, 6, v4
	v_mad_i64_i32 v[28:29], s[20:21], v28, s15, v[8:9]
	global_load_dword v28, v[28:29], off nt
	s_and_b64 vcc, exec, s[0:1]
	s_cbranch_vccnz .LBB0_7
	global_load_dword v17, v[6:7], off offset:28
	s_branch .LBB0_7

; __device__ __forceinline__ void transpose_w(const int wv, LAS unsigned char* lds, const float* __restrict__ w, bf16_t* __restrict__ wt, int K, int N, const float* __restrict__ gk, int slo, int shi, float scale) {
;     ...
;         float v[8];
; #pragma unroll
;         for (int j = 0; j < 8; ++j) { float g = gk ? gk[k0 + j] : 1.0f; v[j] = w[(size_t)(k0 + j) * N + n] * g; }
; __global__ void __launch_bounds__(512, 2) mega(Params p_unused) {
;     ...
;         transpose_w(wv, lds, kp->w_up, WSP(bf16_t, WS_WUP), DM, DFF, kp->norm2_g, 0, 0, 1.f);
.Lwu_38:
	s_lshl_b32 s19, s19, 6
	v_or_b32_e32 v6, s19, v10
	v_ashrrev_i32_e32 v7, 31, v6
	v_lshl_add_u64 v[6:7], v[6:7], 2, s[6:7]
	v_lshlrev_b64 v[18:19], 14, v[4:5]
	v_lshl_add_u64 v[18:19], v[6:7], 0, v[18:19]
	global_load_dword v5, v[18:19], off nt
	s_and_b64 vcc, exec, s[0:1]
	s_cbranch_vccnz .Lwu_40
	global_load_dword v15, v[8:9], off offset:4
.Lwu_40:
	v_add_u32_e32 v18, 1, v4
	v_ashrrev_i32_e32 v19, 31, v18
	v_lshlrev_b64 v[18:19], 14, v[18:19]
	v_lshl_add_u64 v[18:19], v[6:7], 0, v[18:19]
	global_load_dword v17, v[18:19], off nt
	v_mov_b32_e32 v18, 1.0
	s_and_b64 vcc, exec, s[0:1]
	v_mov_b32_e32 v19, 1.0
	s_cbranch_vccnz .Lwu_42
	global_load_dword v19, v[8:9], off offset:8
.Lwu_42:
	v_add_u32_e32 v20, 2, v4
	v_ashrrev_i32_e32 v21, 31, v20
	v_lshlrev_b64 v[20:21], 14, v[20:21]
	v_lshl_add_u64 v[20:21], v[6:7], 0, v[20:21]
	global_load_dword v20, v[20:21], off nt
	s_and_b64 vcc, exec, s[0:1]
	s_cbranch_vccnz .Lwu_44
	global_load_dword v18, v[8:9], off offset:12
.Lwu_44:
	v_add_u32_e32 v22, 3, v4
	v_ashrrev_i32_e32 v23, 31, v22
	v_lshlrev_b64 v[22:23], 14, v[22:23]
	v_lshl_add_u64 v[22:23], v[6:7], 0, v[22:23]
	global_load_dword v22, v[22:23], off nt
	v_mov_b32_e32 v23, 1.0
	s_and_b64 vcc, exec, s[0:1]
	v_mov_b32_e32 v24, 1.0
	s_cbranch_vccnz .Lwu_46
	global_load_dword v24, v[8:9], off offset:16
.Lwu_46:
	v_add_u32_e32 v26, 4, v4
	v_ashrrev_i32_e32 v27, 31, v26
	v_lshlrev_b64 v[26:27], 14, v[26:27]
	v_lshl_add_u64 v[26:27], v[6:7], 0, v[26:27]
	global_load_dword v25, v[26:27], off nt
	s_and_b64 vcc, exec, s[0:1]
	s_cbranch_vccnz .Lwu_48
	global_load_dword v23, v[8:9], off offset:20
.Lwu_48:
	v_add_u32_e32 v26, 5, v4
	v_ashrrev_i32_e32 v27, 31, v26
	v_lshlrev_b64 v[26:27], 14, v[26:27]
	v_lshl_add_u64 v[26:27], v[6:7], 0, v[26:27]
	global_load_dword v26, v[26:27], off nt
	v_mov_b32_e32 v21, 1.0
	s_and_b64 vcc, exec, s[0:1]
	v_mov_b32_e32 v27, 1.0
	s_cbranch_vccnz .Lwu_50
	global_load_dword v27, v[8:9], off offset:24
.Lwu_50:
	v_add_u32_e32 v28, 6, v4
	v_ashrrev_i32_e32 v29, 31, v28
	v_lshlrev_b64 v[28:29], 14, v[28:29]
	v_lshl_add_u64 v[28:29], v[6:7], 0, v[28:29]
	global_load_dword v28, v[28:29], off nt
	s_and_b64 vcc, exec, s[0:1]
	s_cbranch_vccnz .Lwu_35
	global_load_dword v21, v[8:9], off offset:28
	s_branch .Lwu_35
	s_branch .Lwin_wait
